# PROJ unit order: groups of 4 row tiles x 20 column tiles (per-XCD round = 4 rows x 8 cols) instead of 8 x 4 (run 1)
# speedup vs baseline: 1.0096x; 1.0096x over previous
;     __device__ bool next(int i, Unit& u) const { if (r0 + i >= r1) return false; return base.next(r0 + i, u); }
;     __device__ bool next(int i, Unit& u) const { const int L = i * G + c; if (L >= 256) return false; u.pm = L; u.pn = L >> 3; return true; }
;     __device__ bool next(int i, Unit& u) const {
;         const long L = (long)i * G + c; if (L >= nwg) return false;
;         int wgid = (int)L; { const int q = nwg / NXCD, r = nwg % NXCD, xcd = wgid % NXCD, off = wgid / NXCD; wgid = (xcd < r ? xcd * (q + 1) : r * (q + 1) + (xcd - r) * q) + off; }
;         const int nig = WGM * nN, gid = wgid / nig, fm = gid * WGM, gsz = (nM - fm) < WGM ? (nM - fm) : WGM;
;         u.pm = fm + ((wgid % nig) % gsz); u.pn = (wgid % nig) / gsz; return true;
.LBB0_240:
	v_readlane_b32 s8, v255, 3
	s_cmp_lt_i32 s8, 2
	s_cselect_b64 s[6:7], -1, 0
	s_and_b64 s[16:17], s[6:7], s[4:5]
	s_andn2_b64 vcc, exec, s[16:17]
	v_readlane_b32 s9, v255, 4
	v_readlane_b32 s10, v255, 5
	v_readlane_b32 s11, v255, 6
	s_cbranch_vccnz .LBB0_597
	v_readlane_b32 s2, v255, 9
	s_cmpk_lt_i32 s66, 0xa00
	v_mbcnt_lo_u32_b32 v0, -1, 0
	v_mbcnt_hi_u32_b32 v0, -1, v0
	s_cselect_b64 s[4:5], -1, 0
	v_add_u32_e32 v8, s2, v0
	s_cmpk_gt_i32 s66, 0x9ff
	s_cbranch_scc1 .LBB0_243
	s_ashr_i32 s2, s66, 31
	s_lshr_b32 s2, s2, 29
	s_add_i32 s2, s66, s2
	s_ashr_i32 s6, s2, 3
	s_and_b32 s2, s2, -8
	s_sub_i32 s2, s66, s2
	s_cmp_lt_i32 s2, 0
	s_movk_i32 s7, 0x141
	s_cselect_b32 s7, s7, 0x140
	s_mul_i32 s2, s2, s7
	s_add_i32 s2, s2, s6
	s_mul_hi_i32 s6, s2, 0x66666667
	s_lshr_b32 s7, s6, 31
	s_ashr_i32 s6, s6, 5
	s_add_i32 s6, s6, s7
	s_lshl_b32 s7, s6, 2
	s_mulk_i32 s6, 0x50
	s_sub_i32 s2, s2, s6
	s_and_b32 s9, s2, 3
	s_add_i32 s8, s7, s9
	s_lshr_b32 s6, s2, 2

;     __device__ bool next(int i, Unit& u) const { if (r0 + i >= r1) return false; return base.next(r0 + i, u); }
;     __device__ bool next(int i, Unit& u) const { const int L = i * G + c; if (L >= 256) return false; u.pm = L; u.pn = L >> 3; return true; }
;     __device__ bool next(int i, Unit& u) const {
;         const long L = (long)i * G + c; if (L >= nwg) return false;
;         int wgid = (int)L; { const int q = nwg / NXCD, r = nwg % NXCD, xcd = wgid % NXCD, off = wgid / NXCD; wgid = (xcd < r ? xcd * (q + 1) : r * (q + 1) + (xcd - r) * q) + off; }
;         const int nig = WGM * nN, gid = wgid / nig, fm = gid * WGM, gsz = (nM - fm) < WGM ? (nM - fm) : WGM;
;         u.pm = fm + ((wgid % nig) % gsz); u.pn = (wgid % nig) / gsz; return true;
.LBB0_249:
	s_add_i32 s77, s77, 1
	s_mul_i32 s2, s77, s64
	s_mul_hi_u32 s4, s77, s65
	s_add_i32 s4, s4, s2
	s_mul_i32 s2, s77, s65
	v_readlane_b32 s14, v255, 7
	v_readlane_b32 s15, v255, 8
	s_add_u32 s14, s2, s14
	s_addc_u32 s15, s4, s66
	v_cmp_gt_i64_e32 vcc, s[14:15], v[164:165]
	v_cmp_lt_i64_e64 s[4:5], s[14:15], v[162:163]
	s_cbranch_vccnz .LBB0_251
	s_ashr_i32 s2, s14, 31
	s_lshr_b32 s2, s2, 29
	s_add_i32 s2, s14, s2
	s_ashr_i32 s7, s2, 3
	s_and_b32 s2, s2, -8
	s_sub_i32 s2, s14, s2
	s_cmp_lt_i32 s2, 0
	s_movk_i32 s9, 0x141
	s_cselect_b32 s9, s9, 0x140
	s_mul_i32 s2, s2, s9
	s_add_i32 s2, s2, s7
	s_mul_hi_i32 s7, s2, 0x66666667
	s_lshr_b32 s9, s7, 31
	s_ashr_i32 s7, s7, 5
	s_add_i32 s7, s7, s9
	s_lshl_b32 s9, s7, 2
	s_mulk_i32 s7, 0x50
	s_sub_i32 s2, s2, s7
	s_lshr_b32 s38, s2, 2
	s_and_b32 s2, s2, 3
	s_add_i32 s44, s9, s2
